# P1/P3 K loops: second-buffer A-fragment LDS address via ds_read offset instead of a per-iteration VALU add (as in P4/P5)
# speedup vs baseline: 1.0053x; 1.0009x over previous
.LBB0_118:
	ds_read_b128 v[128:131], v221
	ds_read_b128 v[132:135], v221 offset:1024
	ds_read_b128 v[136:139], v221 offset:2048
	ds_read_b128 v[140:143], v221 offset:3072
	s_add_u32 s8, s6, 0xfff80080
	s_addc_u32 s9, s7, -1
	s_cmp_eq_u32 s53, 28
	s_cselect_b32 s11, s5, s9
	s_cselect_b32 s10, s33, s8
	s_cselect_b32 s9, s43, s52
	s_cselect_b32 s8, s45, s51

	s_add_i32 m0, s58, 0xc000
	ds_read_b128 v[144:147], v222
	ds_read_b128 v[148:151], v222 offset:1024
	ds_read_b128 v[152:155], v222 offset:2048
	ds_read_b128 v[156:159], v222 offset:3072
	ds_read_b128 v[160:163], v222 offset:4096
	ds_read_b128 v[164:167], v222 offset:5120
	ds_read_b128 v[190:193], v222 offset:6144
	ds_read_b128 v[194:197], v222 offset:7168
	global_load_lds_dwordx4 v182, s[6:7]
	s_add_i32 m0, s58, 0xe000
	s_nop 0

	global_load_lds_dwordx4 v184, s[6:7]
	s_waitcnt lgkmcnt(8)
	s_barrier
	s_waitcnt lgkmcnt(0)


	v_mfma_f32_16x16x32_bf16 v[124:127], v[128:131], v[144:147], v[124:127]
	v_mfma_f32_16x16x32_bf16 v[116:119], v[136:139], v[144:147], v[116:119]
	v_mfma_f32_16x16x32_bf16 v[108:111], v[128:131], v[152:155], v[108:111]
	v_mfma_f32_16x16x32_bf16 v[100:103], v[136:139], v[152:155], v[100:103]
	v_mfma_f32_16x16x32_bf16 v[92:95], v[128:131], v[160:163], v[92:95]
	v_mfma_f32_16x16x32_bf16 v[84:87], v[136:139], v[160:163], v[84:87]
	v_mfma_f32_16x16x32_bf16 v[76:79], v[128:131], v[190:193], v[76:79]
	v_mfma_f32_16x16x32_bf16 v[68:71], v[136:139], v[190:193], v[68:71]
	v_mfma_f32_16x16x32_bf16 v[124:127], v[132:135], v[148:151], v[124:127]
	v_mfma_f32_16x16x32_bf16 v[116:119], v[140:143], v[148:151], v[116:119]
	v_mfma_f32_16x16x32_bf16 v[108:111], v[132:135], v[156:159], v[108:111]
	v_mfma_f32_16x16x32_bf16 v[100:103], v[140:143], v[156:159], v[100:103]
	v_mfma_f32_16x16x32_bf16 v[92:95], v[132:135], v[164:167], v[92:95]
	v_mfma_f32_16x16x32_bf16 v[84:87], v[140:143], v[164:167], v[84:87]
	v_mfma_f32_16x16x32_bf16 v[76:79], v[132:135], v[194:197], v[76:79]
	v_mfma_f32_16x16x32_bf16 v[68:71], v[140:143], v[194:197], v[68:71]

	s_barrier
	s_add_i32 s54, s81, s57
	s_add_u32 s66, s8, s20
	s_addc_u32 s67, s9, s21
	s_mov_b32 m0, s54
	ds_read_b128 v[198:201], v223
	ds_read_b128 v[202:205], v223 offset:1024
	ds_read_b128 v[206:209], v223 offset:2048
	ds_read_b128 v[226:229], v223 offset:3072
	global_load_lds_dwordx4 v172, s[8:9]
	s_add_i32 m0, s54, 0x2000
	s_nop 0

	global_load_lds_dwordx4 v174, s[8:9]
	s_barrier
	s_waitcnt lgkmcnt(0)


	v_mfma_f32_16x16x32_bf16 v[120:123], v[198:201], v[144:147], v[120:123]
	v_mfma_f32_16x16x32_bf16 v[112:115], v[206:209], v[144:147], v[112:115]
	v_mfma_f32_16x16x32_bf16 v[104:107], v[198:201], v[152:155], v[104:107]
	v_mfma_f32_16x16x32_bf16 v[96:99], v[206:209], v[152:155], v[96:99]
	v_mfma_f32_16x16x32_bf16 v[88:91], v[198:201], v[160:163], v[88:91]
	v_mfma_f32_16x16x32_bf16 v[80:83], v[206:209], v[160:163], v[80:83]
	v_mfma_f32_16x16x32_bf16 v[72:75], v[198:201], v[190:193], v[72:75]
	v_mfma_f32_16x16x32_bf16 v[64:67], v[206:209], v[190:193], v[64:67]
	v_mfma_f32_16x16x32_bf16 v[120:123], v[202:205], v[148:151], v[120:123]
	v_mfma_f32_16x16x32_bf16 v[112:115], v[226:229], v[148:151], v[112:115]
	v_mfma_f32_16x16x32_bf16 v[104:107], v[202:205], v[156:159], v[104:107]
	v_mfma_f32_16x16x32_bf16 v[96:99], v[226:229], v[156:159], v[96:99]
	v_mfma_f32_16x16x32_bf16 v[88:91], v[202:205], v[164:167], v[88:91]
	v_mfma_f32_16x16x32_bf16 v[80:83], v[226:229], v[164:167], v[80:83]
	v_mfma_f32_16x16x32_bf16 v[72:75], v[202:205], v[194:197], v[72:75]
	v_mfma_f32_16x16x32_bf16 v[64:67], v[226:229], v[194:197], v[64:67]

	s_mov_b32 m0, s58
	s_add_u32 s68, s10, s20
	s_addc_u32 s69, s11, s21
	s_barrier
	ds_read_b128 v[144:147], v222 offset:16384
	ds_read_b128 v[148:151], v222 offset:17408
	ds_read_b128 v[152:155], v222 offset:18432
	ds_read_b128 v[156:159], v222 offset:19456
	ds_read_b128 v[160:163], v222 offset:20480
	ds_read_b128 v[164:167], v222 offset:21504
	ds_read_b128 v[190:193], v222 offset:22528
	ds_read_b128 v[194:197], v222 offset:23552
	global_load_lds_dwordx4 v172, s[10:11]
	s_mov_b32 m0, s59
	s_nop 0

	global_load_lds_dwordx4 v174, s[10:11]
	s_barrier
	s_waitcnt lgkmcnt(0)


	v_mfma_f32_16x16x32_bf16 v[60:63], v[128:131], v[144:147], v[60:63]
	v_mfma_f32_16x16x32_bf16 v[52:55], v[136:139], v[144:147], v[52:55]
	v_mfma_f32_16x16x32_bf16 v[44:47], v[128:131], v[152:155], v[44:47]
	v_mfma_f32_16x16x32_bf16 v[36:39], v[136:139], v[152:155], v[36:39]
	v_mfma_f32_16x16x32_bf16 v[28:31], v[128:131], v[160:163], v[28:31]
	v_mfma_f32_16x16x32_bf16 v[20:23], v[136:139], v[160:163], v[20:23]
	v_mfma_f32_16x16x32_bf16 v[12:15], v[128:131], v[190:193], v[12:15]
	v_mfma_f32_16x16x32_bf16 v[4:7], v[136:139], v[190:193], v[4:7]
	v_mfma_f32_16x16x32_bf16 v[60:63], v[132:135], v[148:151], v[60:63]
	v_mfma_f32_16x16x32_bf16 v[52:55], v[140:143], v[148:151], v[52:55]
	v_mfma_f32_16x16x32_bf16 v[44:47], v[132:135], v[156:159], v[44:47]
	v_mfma_f32_16x16x32_bf16 v[36:39], v[140:143], v[156:159], v[36:39]
	v_mfma_f32_16x16x32_bf16 v[28:31], v[132:135], v[164:167], v[28:31]
	v_mfma_f32_16x16x32_bf16 v[20:23], v[140:143], v[164:167], v[20:23]
	v_mfma_f32_16x16x32_bf16 v[12:15], v[132:135], v[194:197], v[12:15]
	v_mfma_f32_16x16x32_bf16 v[4:7], v[140:143], v[194:197], v[4:7]

	s_barrier
	s_add_u32 s54, s8, 0x80000
	s_addc_u32 s55, s9, 0
	s_add_i32 vcc_lo, s30, s57
	s_mov_b32 m0, vcc_lo
	s_nop 0

	global_load_lds_dwordx4 v172, s[54:55]
	s_add_i32 m0, vcc_lo, 0x2000
	s_nop 0

	global_load_lds_dwordx4 v174, s[54:55]
	s_waitcnt vmcnt(6)
	s_barrier

	v_mfma_f32_16x16x32_bf16 v[56:59], v[198:201], v[144:147], v[56:59]
	v_mfma_f32_16x16x32_bf16 v[48:51], v[206:209], v[144:147], v[48:51]
	v_mfma_f32_16x16x32_bf16 v[40:43], v[198:201], v[152:155], v[40:43]
	v_mfma_f32_16x16x32_bf16 v[32:35], v[206:209], v[152:155], v[32:35]
	v_mfma_f32_16x16x32_bf16 v[24:27], v[198:201], v[160:163], v[24:27]
	v_mfma_f32_16x16x32_bf16 v[16:19], v[206:209], v[160:163], v[16:19]
	v_mfma_f32_16x16x32_bf16 v[8:11], v[198:201], v[190:193], v[8:11]
	v_mfma_f32_16x16x32_bf16 v[0:3], v[206:209], v[190:193], v[0:3]
	v_mfma_f32_16x16x32_bf16 v[56:59], v[202:205], v[148:151], v[56:59]
	v_mfma_f32_16x16x32_bf16 v[48:51], v[226:229], v[148:151], v[48:51]
	v_mfma_f32_16x16x32_bf16 v[40:43], v[202:205], v[156:159], v[40:43]
	v_mfma_f32_16x16x32_bf16 v[32:35], v[226:229], v[156:159], v[32:35]
	v_mfma_f32_16x16x32_bf16 v[24:27], v[202:205], v[164:167], v[24:27]
	v_mfma_f32_16x16x32_bf16 v[16:19], v[226:229], v[164:167], v[16:19]
	v_mfma_f32_16x16x32_bf16 v[8:11], v[202:205], v[194:197], v[8:11]
	v_mfma_f32_16x16x32_bf16 v[0:3], v[226:229], v[194:197], v[0:3]

	s_add_i32 s54, 0, 0x18000

	s_barrier
	ds_read_b128 v[128:131], v221 offset:32768
	ds_read_b128 v[132:135], v221 offset:33792
	ds_read_b128 v[136:139], v221 offset:34816
	ds_read_b128 v[140:143], v221 offset:35840
	s_add_u32 s10, s10, 0x80000
	s_addc_u32 s11, s11, 0
	s_mov_b32 m0, s2

	ds_read_b128 v[144:147], v222 offset:32768
	ds_read_b128 v[148:151], v222 offset:33792
	ds_read_b128 v[152:155], v222 offset:34816
	ds_read_b128 v[156:159], v222 offset:35840
	ds_read_b128 v[160:163], v222 offset:36864
	ds_read_b128 v[164:167], v222 offset:37888
	ds_read_b128 v[190:193], v222 offset:38912
	ds_read_b128 v[194:197], v222 offset:39936
	global_load_lds_dwordx4 v172, s[10:11]
	s_mov_b32 m0, s3
	s_nop 0

	global_load_lds_dwordx4 v174, s[10:11]
	s_waitcnt lgkmcnt(8)
	s_barrier
	s_waitcnt lgkmcnt(0)


	v_mfma_f32_16x16x32_bf16 v[124:127], v[128:131], v[144:147], v[124:127]
	v_mfma_f32_16x16x32_bf16 v[116:119], v[136:139], v[144:147], v[116:119]
	v_mfma_f32_16x16x32_bf16 v[108:111], v[128:131], v[152:155], v[108:111]
	v_mfma_f32_16x16x32_bf16 v[100:103], v[136:139], v[152:155], v[100:103]
	v_mfma_f32_16x16x32_bf16 v[92:95], v[128:131], v[160:163], v[92:95]
	v_mfma_f32_16x16x32_bf16 v[84:87], v[136:139], v[160:163], v[84:87]
	v_mfma_f32_16x16x32_bf16 v[76:79], v[128:131], v[190:193], v[76:79]
	v_mfma_f32_16x16x32_bf16 v[68:71], v[136:139], v[190:193], v[68:71]
	v_mfma_f32_16x16x32_bf16 v[124:127], v[132:135], v[148:151], v[124:127]
	v_mfma_f32_16x16x32_bf16 v[116:119], v[140:143], v[148:151], v[116:119]
	v_mfma_f32_16x16x32_bf16 v[108:111], v[132:135], v[156:159], v[108:111]
	v_mfma_f32_16x16x32_bf16 v[100:103], v[140:143], v[156:159], v[100:103]
	v_mfma_f32_16x16x32_bf16 v[92:95], v[132:135], v[164:167], v[92:95]
	v_mfma_f32_16x16x32_bf16 v[84:87], v[140:143], v[164:167], v[84:87]
	v_mfma_f32_16x16x32_bf16 v[76:79], v[132:135], v[194:197], v[76:79]
	v_mfma_f32_16x16x32_bf16 v[68:71], v[140:143], v[194:197], v[68:71]

	s_barrier
	s_add_i32 s10, 0, 0x1c000
	s_add_i32 s11, s54, s57


	s_mov_b32 m0, s11
	ds_read_b128 v[198:201], v223 offset:32768
	ds_read_b128 v[202:205], v223 offset:33792
	ds_read_b128 v[206:209], v223 offset:34816
	ds_read_b128 v[226:229], v223 offset:35840
	global_load_lds_dwordx4 v172, s[66:67]
	s_add_i32 m0, s11, 0x2000
	s_nop 0

	global_load_lds_dwordx4 v174, s[66:67]
	s_barrier
	s_waitcnt lgkmcnt(0)


	v_mfma_f32_16x16x32_bf16 v[120:123], v[198:201], v[144:147], v[120:123]
	v_mfma_f32_16x16x32_bf16 v[112:115], v[206:209], v[144:147], v[112:115]
	v_mfma_f32_16x16x32_bf16 v[104:107], v[198:201], v[152:155], v[104:107]
	v_mfma_f32_16x16x32_bf16 v[96:99], v[206:209], v[152:155], v[96:99]
	v_mfma_f32_16x16x32_bf16 v[88:91], v[198:201], v[160:163], v[88:91]
	v_mfma_f32_16x16x32_bf16 v[80:83], v[206:209], v[160:163], v[80:83]
	v_mfma_f32_16x16x32_bf16 v[72:75], v[198:201], v[190:193], v[72:75]
	v_mfma_f32_16x16x32_bf16 v[64:67], v[206:209], v[190:193], v[64:67]
	v_mfma_f32_16x16x32_bf16 v[120:123], v[202:205], v[148:151], v[120:123]
	v_mfma_f32_16x16x32_bf16 v[112:115], v[226:229], v[148:151], v[112:115]
	v_mfma_f32_16x16x32_bf16 v[104:107], v[202:205], v[156:159], v[104:107]
	v_mfma_f32_16x16x32_bf16 v[96:99], v[226:229], v[156:159], v[96:99]
	v_mfma_f32_16x16x32_bf16 v[88:91], v[202:205], v[164:167], v[88:91]
	v_mfma_f32_16x16x32_bf16 v[80:83], v[226:229], v[164:167], v[80:83]
	v_mfma_f32_16x16x32_bf16 v[72:75], v[202:205], v[194:197], v[72:75]
	v_mfma_f32_16x16x32_bf16 v[64:67], v[226:229], v[194:197], v[64:67]

	s_mov_b32 m0, s96

	s_barrier
	ds_read_b128 v[144:147], v222 offset:49152
	ds_read_b128 v[148:151], v222 offset:50176
	ds_read_b128 v[152:155], v222 offset:51200
	ds_read_b128 v[156:159], v222 offset:52224
	ds_read_b128 v[160:163], v222 offset:53248
	ds_read_b128 v[164:167], v222 offset:54272
	ds_read_b128 v[190:193], v222 offset:55296
	ds_read_b128 v[194:197], v222 offset:56320
	global_load_lds_dwordx4 v172, s[68:69]
	s_mov_b32 m0, s97
	s_nop 0

	global_load_lds_dwordx4 v174, s[68:69]
	s_barrier
	s_waitcnt lgkmcnt(0)


	v_mfma_f32_16x16x32_bf16 v[60:63], v[128:131], v[144:147], v[60:63]
	v_mfma_f32_16x16x32_bf16 v[52:55], v[136:139], v[144:147], v[52:55]
	v_mfma_f32_16x16x32_bf16 v[44:47], v[128:131], v[152:155], v[44:47]
	v_mfma_f32_16x16x32_bf16 v[36:39], v[136:139], v[152:155], v[36:39]
	v_mfma_f32_16x16x32_bf16 v[28:31], v[128:131], v[160:163], v[28:31]
	v_mfma_f32_16x16x32_bf16 v[20:23], v[136:139], v[160:163], v[20:23]
	v_mfma_f32_16x16x32_bf16 v[12:15], v[128:131], v[190:193], v[12:15]
	v_mfma_f32_16x16x32_bf16 v[4:7], v[136:139], v[190:193], v[4:7]
	v_mfma_f32_16x16x32_bf16 v[60:63], v[132:135], v[148:151], v[60:63]
	v_mfma_f32_16x16x32_bf16 v[52:55], v[140:143], v[148:151], v[52:55]
	v_mfma_f32_16x16x32_bf16 v[44:47], v[132:135], v[156:159], v[44:47]
	v_mfma_f32_16x16x32_bf16 v[36:39], v[140:143], v[156:159], v[36:39]
	v_mfma_f32_16x16x32_bf16 v[28:31], v[132:135], v[164:167], v[28:31]
	v_mfma_f32_16x16x32_bf16 v[20:23], v[140:143], v[164:167], v[20:23]
	v_mfma_f32_16x16x32_bf16 v[12:15], v[132:135], v[194:197], v[12:15]
	v_mfma_f32_16x16x32_bf16 v[4:7], v[140:143], v[194:197], v[4:7]

	s_barrier
	s_add_u32 s8, s8, 0x80080
	s_addc_u32 s9, s9, 0
	s_add_i32 s10, s10, s57
	s_mov_b32 m0, s10
	s_nop 0

	global_load_lds_dwordx4 v172, s[8:9]
	s_add_i32 m0, s10, 0x2000
	s_nop 0

	global_load_lds_dwordx4 v174, s[8:9]
	s_waitcnt vmcnt(6)
	s_barrier

	v_mfma_f32_16x16x32_bf16 v[56:59], v[198:201], v[144:147], v[56:59]
	v_mfma_f32_16x16x32_bf16 v[48:51], v[206:209], v[144:147], v[48:51]
	v_mfma_f32_16x16x32_bf16 v[40:43], v[198:201], v[152:155], v[40:43]
	v_mfma_f32_16x16x32_bf16 v[32:35], v[206:209], v[152:155], v[32:35]
	v_mfma_f32_16x16x32_bf16 v[24:27], v[198:201], v[160:163], v[24:27]
	v_mfma_f32_16x16x32_bf16 v[16:19], v[206:209], v[160:163], v[16:19]
	v_mfma_f32_16x16x32_bf16 v[8:11], v[198:201], v[190:193], v[8:11]
	v_mfma_f32_16x16x32_bf16 v[0:3], v[206:209], v[190:193], v[0:3]
	v_mfma_f32_16x16x32_bf16 v[56:59], v[202:205], v[148:151], v[56:59]
	v_mfma_f32_16x16x32_bf16 v[48:51], v[226:229], v[148:151], v[48:51]
	v_mfma_f32_16x16x32_bf16 v[40:43], v[202:205], v[156:159], v[40:43]
	v_mfma_f32_16x16x32_bf16 v[32:35], v[226:229], v[156:159], v[32:35]
	v_mfma_f32_16x16x32_bf16 v[24:27], v[202:205], v[164:167], v[24:27]
	v_mfma_f32_16x16x32_bf16 v[16:19], v[226:229], v[164:167], v[16:19]
	v_mfma_f32_16x16x32_bf16 v[8:11], v[202:205], v[194:197], v[8:11]
	v_mfma_f32_16x16x32_bf16 v[0:3], v[226:229], v[194:197], v[0:3]

	s_add_i32 s53, s53, 2
	s_add_u32 s6, s6, 0x100
	s_addc_u32 s7, s7, 0
	s_add_u32 s51, s51, 0x100
	s_addc_u32 s52, s52, 0
	s_cmp_gt_u32 s53, 29
	s_barrier
	s_cbranch_scc0 .LBB0_118
	v_mov_b32_e32 v142, v210
	v_mov_b32_e32 v143, v169
	s_lshl_b32 s33, s4, 8
	s_add_i32 s33, s33, s34
	v_lshl_add_u32 v133, v142, 4, v143
	v_ashrrev_i32_e32 v198, 2, v133
	v_and_b32_e32 v192, 3, v143
	v_and_b32_e32 v128, -4, v133
	s_cmp_gt_i32 s4, 30
	v_lshl_add_u32 v226, v192, 6, v128
	v_add_u32_e32 v190, s33, v198
	s_cselect_b64 s[52:53], -1, 0
	s_cmp_gt_i32 s50, 8
	s_mov_b64 s[4:5], -1
	s_cbranch_scc0 .LBB0_419
	s_cmp_lg_u32 s50, 9
	s_cbranch_scc0 .LBB0_225
	s_cmp_gt_u32 s50, 25
	s_cbranch_scc0 .LBB0_127
	v_mul_f32_e32 v130, 0xbfb8aa3b, v120
	v_mul_f32_e32 v131, 0xbfb8aa3b, v121
	v_mul_f32_e32 v132, 0xbfb8aa3b, v122
	v_mul_f32_e32 v134, 0xbfb8aa3b, v123
	v_mul_f32_e32 v135, 0xbfb8aa3b, v112
	v_mul_f32_e32 v136, 0xbfb8aa3b, v113
	v_mul_f32_e32 v137, 0xbfb8aa3b, v114
	v_mul_f32_e32 v138, 0xbfb8aa3b, v115
	v_mul_f32_e32 v139, 0xbfb8aa3b, v104
	v_mul_f32_e32 v140, 0xbfb8aa3b, v105
	v_mul_f32_e32 v141, 0xbfb8aa3b, v106
	v_mul_f32_e32 v144, 0xbfb8aa3b, v107
	v_mul_f32_e32 v145, 0xbfb8aa3b, v96
	v_mul_f32_e32 v146, 0xbfb8aa3b, v97
	v_mul_f32_e32 v147, 0xbfb8aa3b, v98
	v_mul_f32_e32 v148, 0xbfb8aa3b, v99
	v_mul_f32_e32 v149, 0xbfb8aa3b, v88
	v_mul_f32_e32 v150, 0xbfb8aa3b, v89
	v_mul_f32_e32 v151, 0xbfb8aa3b, v90
	v_mul_f32_e32 v152, 0xbfb8aa3b, v91
	v_mul_f32_e32 v153, 0xbfb8aa3b, v80
	v_mul_f32_e32 v154, 0xbfb8aa3b, v81
	v_mul_f32_e32 v155, 0xbfb8aa3b, v82
	v_mul_f32_e32 v180, 0xbfb8aa3b, v83
	v_mul_f32_e32 v206, 0xbfb8aa3b, v72
	v_mul_f32_e32 v207, 0xbfb8aa3b, v73
	v_mul_f32_e32 v208, 0xbfb8aa3b, v74
	v_mul_f32_e32 v209, 0xbfb8aa3b, v75
	v_mul_f32_e32 v227, 0xbfb8aa3b, v64
	v_mul_f32_e32 v228, 0xbfb8aa3b, v65
	v_mul_f32_e32 v229, 0xbfb8aa3b, v66
	v_mul_f32_e32 v230, 0xbfb8aa3b, v67
	v_exp_f32_e32 v205, v130
	v_exp_f32_e32 v204, v131
	v_exp_f32_e32 v203, v132
	v_exp_f32_e32 v202, v134
	v_exp_f32_e32 v200, v135
	v_exp_f32_e32 v199, v136
	v_exp_f32_e32 v197, v137
	v_exp_f32_e32 v196, v138
	v_exp_f32_e32 v195, v139
	v_exp_f32_e32 v194, v140
	v_exp_f32_e32 v193, v141
	v_exp_f32_e32 v167, v144
	v_exp_f32_e32 v166, v145
	v_exp_f32_e32 v165, v146
	v_exp_f32_e32 v164, v147
	v_exp_f32_e32 v163, v148
	v_exp_f32_e32 v162, v149
	v_exp_f32_e32 v161, v150
	v_exp_f32_e32 v160, v151
	v_exp_f32_e32 v159, v152
	v_exp_f32_e32 v158, v153
	v_exp_f32_e32 v157, v154
	v_exp_f32_e32 v156, v155
	v_exp_f32_e32 v155, v180
	v_exp_f32_e32 v154, v206
	v_exp_f32_e32 v153, v207
	v_exp_f32_e32 v152, v208
	v_exp_f32_e32 v151, v209
	v_exp_f32_e32 v150, v227
	v_exp_f32_e32 v149, v228
	v_exp_f32_e32 v148, v229
	v_exp_f32_e32 v147, v230
	v_ashrrev_i32_e32 v191, 31, v190
	s_cmp_lt_u32 s50, 42
	v_lshlrev_b32_e32 v201, 2, v192
	v_lshlrev_b64 v[128:129], 12, v[190:191]
	v_mul_f32_e32 v146, 0xbfb8aa3b, v56
	v_mul_f32_e32 v145, 0xbfb8aa3b, v57
	v_mul_f32_e32 v144, 0xbfb8aa3b, v58
	v_mul_f32_e32 v141, 0xbfb8aa3b, v59
	v_mul_f32_e32 v140, 0xbfb8aa3b, v48
	v_mul_f32_e32 v139, 0xbfb8aa3b, v49
	v_mul_f32_e32 v138, 0xbfb8aa3b, v50
	v_mul_f32_e32 v137, 0xbfb8aa3b, v51
	v_mul_f32_e32 v136, 0xbfb8aa3b, v40
	v_mul_f32_e32 v135, 0xbfb8aa3b, v41
	v_mul_f32_e32 v134, 0xbfb8aa3b, v42
	v_mul_f32_e32 v132, 0xbfb8aa3b, v43
	s_cbranch_scc1 .LBB0_124
	v_mul_f32_e32 v130, 0xbfb8aa3b, v124
	v_mul_f32_e32 v131, 0xbfb8aa3b, v125
	v_mul_f32_e32 v206, 0xbfb8aa3b, v126
	v_mul_f32_e32 v207, 0xbfb8aa3b, v127
	v_exp_f32_e32 v130, v130
	v_exp_f32_e32 v131, v131
	v_exp_f32_e32 v206, v206
	v_exp_f32_e32 v207, v207
	v_add_f32_e32 v130, 1.0, v130
	v_add_f32_e32 v131, 1.0, v131
	v_add_f32_e32 v206, 1.0, v206
	v_add_f32_e32 v207, 1.0, v207
	v_rcp_f32_e32 v130, v130
	v_rcp_f32_e32 v131, v131
	v_rcp_f32_e32 v206, v206
	v_rcp_f32_e32 v207, v207
	s_lshl_b32 s4, s50, 8
	v_cvt_pk_bf16_f32 v130, v130, v131
	s_add_i32 s4, s28, s4
	v_cvt_pk_bf16_f32 v131, v206, v207
	ds_bpermute_b32 v206, v226, v130
	ds_bpermute_b32 v207, v226, v131
	v_or_b32_e32 v180, s4, v201
	v_lshl_add_u64 v[130:131], s[40:41], 0, v[128:129]
	v_lshlrev_b64 v[208:209], 1, v[180:181]
	v_lshl_add_u64 v[130:131], v[130:131], 0, v[208:209]
	s_waitcnt lgkmcnt(0)
	global_store_dwordx2 v[130:131], v[206:207], off
	v_mul_f32_e32 v180, 0xbfb8aa3b, v116
	v_mul_f32_e32 v206, 0xbfb8aa3b, v117
	v_mul_f32_e32 v207, 0xbfb8aa3b, v118
	v_mul_f32_e32 v208, 0xbfb8aa3b, v119
	v_exp_f32_e32 v180, v180
	v_exp_f32_e32 v206, v206
	v_exp_f32_e32 v207, v207
	v_exp_f32_e32 v208, v208
	v_add_f32_e32 v180, 1.0, v180
	v_add_f32_e32 v206, 1.0, v206
	v_add_f32_e32 v207, 1.0, v207
	v_add_f32_e32 v208, 1.0, v208
	v_rcp_f32_e32 v180, v180
	v_rcp_f32_e32 v206, v206
	v_rcp_f32_e32 v207, v207
	v_rcp_f32_e32 v208, v208
	s_mov_b64 s[4:5], 0x10000
	v_cvt_pk_bf16_f32 v180, v180, v206
	ds_bpermute_b32 v206, v226, v180
	v_cvt_pk_bf16_f32 v207, v207, v208
	ds_bpermute_b32 v207, v226, v207
	v_add_f32_e32 v180, 1.0, v205
	v_add_f32_e32 v208, 1.0, v202
	v_rcp_f32_e32 v180, v180
	v_rcp_f32_e32 v208, v208
	s_waitcnt lgkmcnt(0)
	global_store_dwordx2 v[130:131], v[206:207], off offset:32
	v_add_f32_e32 v206, 1.0, v204
	v_add_f32_e32 v207, 1.0, v203
	v_rcp_f32_e32 v206, v206
	v_rcp_f32_e32 v207, v207
	v_mul_f32_e32 v227, 0xbfb8aa3b, v103
	v_exp_f32_e32 v227, v227
	v_cvt_pk_bf16_f32 v180, v180, v206
	v_cvt_pk_bf16_f32 v207, v207, v208
	ds_bpermute_b32 v206, v226, v180
	ds_bpermute_b32 v207, v226, v207
	v_add_f32_e32 v180, 1.0, v200
	v_add_f32_e32 v208, 1.0, v196
	v_rcp_f32_e32 v180, v180
	v_rcp_f32_e32 v208, v208
	s_waitcnt lgkmcnt(0)
	global_store_dwordx2 v[130:131], v[206:207], off offset:256
	v_add_f32_e32 v206, 1.0, v199
	v_add_f32_e32 v207, 1.0, v197
	v_rcp_f32_e32 v206, v206
	v_rcp_f32_e32 v207, v207
	v_add_f32_e32 v227, 1.0, v227
	v_rcp_f32_e32 v227, v227
	v_cvt_pk_bf16_f32 v180, v180, v206
	v_cvt_pk_bf16_f32 v207, v207, v208
	ds_bpermute_b32 v206, v226, v180
	ds_bpermute_b32 v207, v226, v207
	v_mul_f32_e32 v180, 0xbfb8aa3b, v108
	v_mul_f32_e32 v208, 0xbfb8aa3b, v111
	v_exp_f32_e32 v180, v180
	v_exp_f32_e32 v208, v208
	s_waitcnt lgkmcnt(0)
	global_store_dwordx2 v[130:131], v[206:207], off offset:288
	v_mul_f32_e32 v206, 0xbfb8aa3b, v109
	v_mul_f32_e32 v207, 0xbfb8aa3b, v110
	v_exp_f32_e32 v206, v206
	v_exp_f32_e32 v207, v207
	v_add_f32_e32 v180, 1.0, v180
	v_add_f32_e32 v208, 1.0, v208
	v_add_f32_e32 v206, 1.0, v206
	v_add_f32_e32 v207, 1.0, v207
	v_rcp_f32_e32 v180, v180
	v_rcp_f32_e32 v206, v206
	v_rcp_f32_e32 v207, v207
	v_rcp_f32_e32 v208, v208
	v_cvt_pk_bf16_f32 v180, v180, v206
	ds_bpermute_b32 v206, v226, v180
	v_cvt_pk_bf16_f32 v207, v207, v208
	ds_bpermute_b32 v207, v226, v207
	v_lshl_add_u64 v[208:209], v[130:131], 0, s[4:5]
	s_mov_b32 s4, 0x10000
	v_add_co_u32_e32 v228, vcc, s4, v130
	v_mul_f32_e32 v180, 0xbfb8aa3b, v100
	s_nop 0
	v_addc_co_u32_e32 v229, vcc, 0, v131, vcc
	s_waitcnt lgkmcnt(0)
	global_store_dwordx2 v[228:229], v[206:207], off
	v_mul_f32_e32 v206, 0xbfb8aa3b, v101
	v_mul_f32_e32 v207, 0xbfb8aa3b, v102
	v_exp_f32_e32 v180, v180
	v_exp_f32_e32 v206, v206
	v_exp_f32_e32 v207, v207
	s_mov_b64 s[4:5], 0x20000
	v_add_f32_e32 v180, 1.0, v180
	v_add_f32_e32 v206, 1.0, v206
	v_add_f32_e32 v207, 1.0, v207
	v_rcp_f32_e32 v180, v180
	v_rcp_f32_e32 v206, v206
	v_rcp_f32_e32 v207, v207
	v_cvt_pk_bf16_f32 v180, v180, v206
	v_cvt_pk_bf16_f32 v207, v207, v227
	ds_bpermute_b32 v206, v226, v180
	ds_bpermute_b32 v207, v226, v207
	v_add_f32_e32 v180, 1.0, v195
	v_add_f32_e32 v227, 1.0, v167
	v_rcp_f32_e32 v180, v180
	v_rcp_f32_e32 v227, v227
	s_waitcnt lgkmcnt(0)
	global_store_dwordx2 v[208:209], v[206:207], off offset:32
	v_add_f32_e32 v206, 1.0, v194
	v_add_f32_e32 v207, 1.0, v193
	v_rcp_f32_e32 v206, v206
	v_rcp_f32_e32 v207, v207
	v_cvt_pk_bf16_f32 v180, v180, v206
	v_cvt_pk_bf16_f32 v207, v207, v227
	ds_bpermute_b32 v206, v226, v180
	ds_bpermute_b32 v207, v226, v207
	v_add_f32_e32 v180, 1.0, v166
	v_add_f32_e32 v227, 1.0, v163
	v_rcp_f32_e32 v180, v180
	v_rcp_f32_e32 v227, v227
	s_waitcnt lgkmcnt(0)
	global_store_dwordx2 v[208:209], v[206:207], off offset:256
	v_add_f32_e32 v206, 1.0, v165
	v_add_f32_e32 v207, 1.0, v164
	v_rcp_f32_e32 v206, v206
	v_rcp_f32_e32 v207, v207
	v_cvt_pk_bf16_f32 v180, v180, v206
	v_cvt_pk_bf16_f32 v207, v207, v227
	ds_bpermute_b32 v206, v226, v180
	ds_bpermute_b32 v207, v226, v207
	v_mul_f32_e32 v180, 0xbfb8aa3b, v92
	v_exp_f32_e32 v180, v180
	v_mul_f32_e32 v227, 0xbfb8aa3b, v87
	v_exp_f32_e32 v227, v227
	s_waitcnt lgkmcnt(0)
	global_store_dwordx2 v[208:209], v[206:207], off offset:288
	v_mul_f32_e32 v206, 0xbfb8aa3b, v93
	v_mul_f32_e32 v207, 0xbfb8aa3b, v94
	v_mul_f32_e32 v208, 0xbfb8aa3b, v95
	v_exp_f32_e32 v206, v206
	v_exp_f32_e32 v207, v207
	v_exp_f32_e32 v208, v208
	v_add_f32_e32 v180, 1.0, v180
	v_add_f32_e32 v206, 1.0, v206
	v_add_f32_e32 v207, 1.0, v207
	v_add_f32_e32 v208, 1.0, v208
	v_rcp_f32_e32 v180, v180
	v_rcp_f32_e32 v206, v206
	v_rcp_f32_e32 v207, v207
	v_rcp_f32_e32 v208, v208
	v_add_f32_e32 v227, 1.0, v227
	v_cvt_pk_bf16_f32 v180, v180, v206
	ds_bpermute_b32 v206, v226, v180
	v_cvt_pk_bf16_f32 v207, v207, v208
	ds_bpermute_b32 v207, v226, v207
	v_lshl_add_u64 v[208:209], v[130:131], 0, s[4:5]
	s_mov_b32 s4, 0x20000
	v_add_co_u32_e32 v228, vcc, s4, v130
	v_mul_f32_e32 v180, 0xbfb8aa3b, v84
	s_nop 0
	v_addc_co_u32_e32 v229, vcc, 0, v131, vcc
	s_waitcnt lgkmcnt(0)
	global_store_dwordx2 v[228:229], v[206:207], off
	v_mul_f32_e32 v206, 0xbfb8aa3b, v85
	v_mul_f32_e32 v207, 0xbfb8aa3b, v86
	v_exp_f32_e32 v180, v180
	v_exp_f32_e32 v206, v206
	v_exp_f32_e32 v207, v207
	v_rcp_f32_e32 v227, v227
	v_add_f32_e32 v180, 1.0, v180
	v_add_f32_e32 v206, 1.0, v206
	v_add_f32_e32 v207, 1.0, v207
	v_rcp_f32_e32 v180, v180
	v_rcp_f32_e32 v206, v206
	v_rcp_f32_e32 v207, v207
	s_mov_b64 s[4:5], 0x30000
	v_cvt_pk_bf16_f32 v180, v180, v206
	v_cvt_pk_bf16_f32 v207, v207, v227
	ds_bpermute_b32 v206, v226, v180
	ds_bpermute_b32 v207, v226, v207
	v_add_f32_e32 v180, 1.0, v162
	v_add_f32_e32 v227, 1.0, v159
	v_rcp_f32_e32 v180, v180
	v_rcp_f32_e32 v227, v227
	s_waitcnt lgkmcnt(0)
	global_store_dwordx2 v[208:209], v[206:207], off offset:32
	v_add_f32_e32 v206, 1.0, v161
	v_add_f32_e32 v207, 1.0, v160
	v_rcp_f32_e32 v206, v206
	v_rcp_f32_e32 v207, v207
	v_cvt_pk_bf16_f32 v180, v180, v206
	v_cvt_pk_bf16_f32 v207, v207, v227
	ds_bpermute_b32 v206, v226, v180
	ds_bpermute_b32 v207, v226, v207
	v_add_f32_e32 v180, 1.0, v158
	v_add_f32_e32 v227, 1.0, v155
	v_rcp_f32_e32 v180, v180
	v_rcp_f32_e32 v227, v227
	s_waitcnt lgkmcnt(0)
	global_store_dwordx2 v[208:209], v[206:207], off offset:256
	v_add_f32_e32 v206, 1.0, v157
	v_add_f32_e32 v207, 1.0, v156
	v_rcp_f32_e32 v206, v206
	v_rcp_f32_e32 v207, v207
	v_cvt_pk_bf16_f32 v180, v180, v206
	v_cvt_pk_bf16_f32 v207, v207, v227
	ds_bpermute_b32 v206, v226, v180
	ds_bpermute_b32 v207, v226, v207
	v_mul_f32_e32 v180, 0xbfb8aa3b, v76
	v_exp_f32_e32 v180, v180
	v_mul_f32_e32 v227, 0xbfb8aa3b, v71
	v_exp_f32_e32 v227, v227
	s_waitcnt lgkmcnt(0)
	global_store_dwordx2 v[208:209], v[206:207], off offset:288
	v_mul_f32_e32 v206, 0xbfb8aa3b, v77
	v_mul_f32_e32 v207, 0xbfb8aa3b, v78
	v_mul_f32_e32 v208, 0xbfb8aa3b, v79
	v_exp_f32_e32 v206, v206
	v_exp_f32_e32 v207, v207
	v_exp_f32_e32 v208, v208
	v_add_f32_e32 v180, 1.0, v180
	v_add_f32_e32 v206, 1.0, v206
	v_add_f32_e32 v207, 1.0, v207
	v_add_f32_e32 v208, 1.0, v208
	v_rcp_f32_e32 v180, v180
	v_rcp_f32_e32 v206, v206
	v_rcp_f32_e32 v207, v207
	v_rcp_f32_e32 v208, v208
	v_add_f32_e32 v227, 1.0, v227
	v_cvt_pk_bf16_f32 v180, v180, v206
	ds_bpermute_b32 v206, v226, v180
	v_cvt_pk_bf16_f32 v207, v207, v208
	ds_bpermute_b32 v207, v226, v207
	v_lshl_add_u64 v[208:209], v[130:131], 0, s[4:5]
	s_mov_b32 s4, 0x30000
	v_add_co_u32_e32 v228, vcc, s4, v130
	v_mul_f32_e32 v180, 0xbfb8aa3b, v68
	s_nop 0
	v_addc_co_u32_e32 v229, vcc, 0, v131, vcc
	s_waitcnt lgkmcnt(0)
	global_store_dwordx2 v[228:229], v[206:207], off
	v_mul_f32_e32 v206, 0xbfb8aa3b, v69
	v_mul_f32_e32 v207, 0xbfb8aa3b, v70
	v_exp_f32_e32 v180, v180
	v_exp_f32_e32 v206, v206
	v_exp_f32_e32 v207, v207
	v_rcp_f32_e32 v227, v227
	v_add_f32_e32 v180, 1.0, v180
	v_add_f32_e32 v206, 1.0, v206
	v_add_f32_e32 v207, 1.0, v207
	v_rcp_f32_e32 v180, v180
	v_rcp_f32_e32 v206, v206
	v_rcp_f32_e32 v207, v207
	s_mov_b64 s[4:5], 0x80000
	v_cvt_pk_bf16_f32 v180, v180, v206
	v_cvt_pk_bf16_f32 v207, v207, v227
	ds_bpermute_b32 v206, v226, v180
	ds_bpermute_b32 v207, v226, v207
	v_add_f32_e32 v180, 1.0, v154
	v_add_f32_e32 v227, 1.0, v151
	v_rcp_f32_e32 v180, v180
	v_rcp_f32_e32 v227, v227
	s_waitcnt lgkmcnt(0)
	global_store_dwordx2 v[208:209], v[206:207], off offset:32
	v_add_f32_e32 v206, 1.0, v153
	v_add_f32_e32 v207, 1.0, v152
	v_rcp_f32_e32 v206, v206
	v_rcp_f32_e32 v207, v207
	v_cvt_pk_bf16_f32 v180, v180, v206
	v_cvt_pk_bf16_f32 v207, v207, v227
	ds_bpermute_b32 v206, v226, v180
	ds_bpermute_b32 v207, v226, v207
	v_add_f32_e32 v180, 1.0, v150
	v_add_f32_e32 v227, 1.0, v147
	v_rcp_f32_e32 v180, v180
	v_rcp_f32_e32 v227, v227
	s_waitcnt lgkmcnt(0)
	global_store_dwordx2 v[208:209], v[206:207], off offset:256
	v_add_f32_e32 v206, 1.0, v149
	v_add_f32_e32 v207, 1.0, v148
	v_rcp_f32_e32 v206, v206
	v_rcp_f32_e32 v207, v207
	v_cvt_pk_bf16_f32 v180, v180, v206
	v_cvt_pk_bf16_f32 v207, v207, v227
	ds_bpermute_b32 v206, v226, v180
	ds_bpermute_b32 v207, v226, v207
	v_mul_f32_e32 v180, 0xbfb8aa3b, v60
	v_exp_f32_e32 v180, v180
	v_mul_f32_e32 v227, 0xbfb8aa3b, v55
	v_exp_f32_e32 v227, v227
	s_waitcnt lgkmcnt(0)
	global_store_dwordx2 v[208:209], v[206:207], off offset:288
	v_mul_f32_e32 v206, 0xbfb8aa3b, v61
	v_mul_f32_e32 v207, 0xbfb8aa3b, v62
	v_mul_f32_e32 v208, 0xbfb8aa3b, v63
	v_exp_f32_e32 v206, v206
	v_exp_f32_e32 v207, v207
	v_exp_f32_e32 v208, v208
	v_add_f32_e32 v180, 1.0, v180
	v_add_f32_e32 v206, 1.0, v206
	v_add_f32_e32 v207, 1.0, v207
	v_add_f32_e32 v208, 1.0, v208
	v_rcp_f32_e32 v180, v180
	v_rcp_f32_e32 v206, v206
	v_rcp_f32_e32 v207, v207
	v_rcp_f32_e32 v208, v208
	v_add_f32_e32 v227, 1.0, v227
	v_cvt_pk_bf16_f32 v180, v180, v206
	ds_bpermute_b32 v206, v226, v180
	v_cvt_pk_bf16_f32 v207, v207, v208
	ds_bpermute_b32 v207, v226, v207
	v_lshl_add_u64 v[208:209], v[130:131], 0, s[4:5]
	s_mov_b32 s4, 0x80000
	v_add_co_u32_e32 v228, vcc, s4, v130
	v_mul_f32_e32 v180, 0xbfb8aa3b, v52
	s_nop 0
	v_addc_co_u32_e32 v229, vcc, 0, v131, vcc
	s_waitcnt lgkmcnt(0)
	global_store_dwordx2 v[228:229], v[206:207], off
	v_mul_f32_e32 v206, 0xbfb8aa3b, v53
	v_mul_f32_e32 v207, 0xbfb8aa3b, v54
	v_exp_f32_e32 v180, v180
	v_exp_f32_e32 v206, v206
	v_exp_f32_e32 v207, v207
	v_rcp_f32_e32 v227, v227
	v_add_f32_e32 v180, 1.0, v180
	v_add_f32_e32 v206, 1.0, v206
	v_add_f32_e32 v207, 1.0, v207
	v_rcp_f32_e32 v180, v180
	v_rcp_f32_e32 v206, v206
	v_rcp_f32_e32 v207, v207
	s_mov_b64 s[4:5], 0x90000
	v_cvt_pk_bf16_f32 v180, v180, v206
	v_cvt_pk_bf16_f32 v207, v207, v227
	ds_bpermute_b32 v206, v226, v180
	ds_bpermute_b32 v207, v226, v207
	v_exp_f32_e32 v180, v146
	v_exp_f32_e32 v227, v141
	s_waitcnt lgkmcnt(0)
	global_store_dwordx2 v[208:209], v[206:207], off offset:32
	v_exp_f32_e32 v206, v145
	v_exp_f32_e32 v207, v144
	v_add_f32_e32 v180, 1.0, v180
	v_add_f32_e32 v227, 1.0, v227
	v_add_f32_e32 v206, 1.0, v206
	v_add_f32_e32 v207, 1.0, v207
	v_rcp_f32_e32 v180, v180
	v_rcp_f32_e32 v206, v206
	v_rcp_f32_e32 v207, v207
	v_rcp_f32_e32 v227, v227
	v_cvt_pk_bf16_f32 v180, v180, v206
	ds_bpermute_b32 v206, v226, v180
	v_cvt_pk_bf16_f32 v207, v207, v227
	ds_bpermute_b32 v207, v226, v207
	v_exp_f32_e32 v180, v140
	v_exp_f32_e32 v227, v137
	s_waitcnt lgkmcnt(0)
	global_store_dwordx2 v[208:209], v[206:207], off offset:256
	v_exp_f32_e32 v206, v139
	v_exp_f32_e32 v207, v138
	v_add_f32_e32 v180, 1.0, v180
	v_add_f32_e32 v227, 1.0, v227
	v_add_f32_e32 v206, 1.0, v206
	v_add_f32_e32 v207, 1.0, v207
	v_rcp_f32_e32 v180, v180
	v_rcp_f32_e32 v206, v206
	v_rcp_f32_e32 v207, v207
	v_rcp_f32_e32 v227, v227
	v_cvt_pk_bf16_f32 v180, v180, v206
	ds_bpermute_b32 v206, v226, v180
	v_cvt_pk_bf16_f32 v207, v207, v227
	ds_bpermute_b32 v207, v226, v207
	v_mul_f32_e32 v180, 0xbfb8aa3b, v44
	v_exp_f32_e32 v180, v180
	v_mul_f32_e32 v227, 0xbfb8aa3b, v39
	v_exp_f32_e32 v227, v227
	s_waitcnt lgkmcnt(0)
	global_store_dwordx2 v[208:209], v[206:207], off offset:288
	v_mul_f32_e32 v206, 0xbfb8aa3b, v45
	v_mul_f32_e32 v207, 0xbfb8aa3b, v46
	v_mul_f32_e32 v208, 0xbfb8aa3b, v47
	v_exp_f32_e32 v206, v206
	v_exp_f32_e32 v207, v207
	v_exp_f32_e32 v208, v208
	v_add_f32_e32 v180, 1.0, v180
	v_add_f32_e32 v206, 1.0, v206
	v_add_f32_e32 v207, 1.0, v207
	v_add_f32_e32 v208, 1.0, v208
	v_rcp_f32_e32 v180, v180
	v_rcp_f32_e32 v206, v206
	v_rcp_f32_e32 v207, v207
	v_rcp_f32_e32 v208, v208
	v_add_f32_e32 v227, 1.0, v227
	v_cvt_pk_bf16_f32 v180, v180, v206
	ds_bpermute_b32 v206, v226, v180
	v_cvt_pk_bf16_f32 v207, v207, v208
	ds_bpermute_b32 v207, v226, v207
	v_lshl_add_u64 v[208:209], v[130:131], 0, s[4:5]
	s_mov_b32 s4, 0x90000
	v_add_co_u32_e32 v228, vcc, s4, v130
	v_mul_f32_e32 v180, 0xbfb8aa3b, v36
	s_nop 0
	v_addc_co_u32_e32 v229, vcc, 0, v131, vcc
	s_waitcnt lgkmcnt(0)
	global_store_dwordx2 v[228:229], v[206:207], off
	v_mul_f32_e32 v206, 0xbfb8aa3b, v37
	v_mul_f32_e32 v207, 0xbfb8aa3b, v38
	v_exp_f32_e32 v180, v180
	v_exp_f32_e32 v206, v206
	v_exp_f32_e32 v207, v207
	v_rcp_f32_e32 v227, v227
	v_add_f32_e32 v180, 1.0, v180
	v_add_f32_e32 v206, 1.0, v206
	v_add_f32_e32 v207, 1.0, v207
	v_rcp_f32_e32 v180, v180
	v_rcp_f32_e32 v206, v206
	v_rcp_f32_e32 v207, v207
	s_mov_b64 s[4:5], 0xa0000
	v_cvt_pk_bf16_f32 v180, v180, v206
	v_cvt_pk_bf16_f32 v207, v207, v227
	ds_bpermute_b32 v206, v226, v180
	ds_bpermute_b32 v207, v226, v207
	v_exp_f32_e32 v180, v136
	v_exp_f32_e32 v227, v132
	s_waitcnt lgkmcnt(0)
	global_store_dwordx2 v[208:209], v[206:207], off offset:32
	v_exp_f32_e32 v206, v135
	v_exp_f32_e32 v207, v134
	v_add_f32_e32 v180, 1.0, v180
	v_add_f32_e32 v227, 1.0, v227
	v_add_f32_e32 v206, 1.0, v206
	v_add_f32_e32 v207, 1.0, v207
	v_rcp_f32_e32 v180, v180
	v_rcp_f32_e32 v206, v206
	v_rcp_f32_e32 v207, v207
	v_rcp_f32_e32 v227, v227
	v_cvt_pk_bf16_f32 v180, v180, v206
	ds_bpermute_b32 v206, v226, v180
	v_cvt_pk_bf16_f32 v207, v207, v227
	ds_bpermute_b32 v207, v226, v207
	v_mul_f32_e32 v180, 0xbfb8aa3b, v32
	v_mul_f32_e32 v227, 0xbfb8aa3b, v35
	v_exp_f32_e32 v180, v180
	v_exp_f32_e32 v227, v227
	s_waitcnt lgkmcnt(0)
	global_store_dwordx2 v[208:209], v[206:207], off offset:256
	v_mul_f32_e32 v206, 0xbfb8aa3b, v33
	v_mul_f32_e32 v207, 0xbfb8aa3b, v34
	v_exp_f32_e32 v206, v206
	v_exp_f32_e32 v207, v207
	v_add_f32_e32 v180, 1.0, v180
	v_add_f32_e32 v227, 1.0, v227
	v_add_f32_e32 v206, 1.0, v206
	v_add_f32_e32 v207, 1.0, v207
	v_rcp_f32_e32 v180, v180
	v_rcp_f32_e32 v206, v206
	v_rcp_f32_e32 v207, v207
	v_rcp_f32_e32 v227, v227
	v_cvt_pk_bf16_f32 v180, v180, v206
	ds_bpermute_b32 v206, v226, v180
	v_cvt_pk_bf16_f32 v207, v207, v227
	ds_bpermute_b32 v207, v226, v207
	v_mul_f32_e32 v180, 0xbfb8aa3b, v28
	v_exp_f32_e32 v180, v180
	v_mul_f32_e32 v227, 0xbfb8aa3b, v23
	v_exp_f32_e32 v227, v227
	s_waitcnt lgkmcnt(0)
	global_store_dwordx2 v[208:209], v[206:207], off offset:288
	v_mul_f32_e32 v206, 0xbfb8aa3b, v29
	v_mul_f32_e32 v207, 0xbfb8aa3b, v30
	v_mul_f32_e32 v208, 0xbfb8aa3b, v31
	v_exp_f32_e32 v206, v206
	v_exp_f32_e32 v207, v207
	v_exp_f32_e32 v208, v208
	v_add_f32_e32 v180, 1.0, v180
	v_add_f32_e32 v206, 1.0, v206
	v_add_f32_e32 v207, 1.0, v207
	v_add_f32_e32 v208, 1.0, v208
	v_rcp_f32_e32 v180, v180
	v_rcp_f32_e32 v206, v206
	v_rcp_f32_e32 v207, v207
	v_rcp_f32_e32 v208, v208
	v_add_f32_e32 v227, 1.0, v227
	v_cvt_pk_bf16_f32 v180, v180, v206
	ds_bpermute_b32 v206, v226, v180
	v_cvt_pk_bf16_f32 v207, v207, v208
	ds_bpermute_b32 v207, v226, v207
	v_lshl_add_u64 v[208:209], v[130:131], 0, s[4:5]
	s_mov_b32 s4, 0xa0000
	v_add_co_u32_e32 v228, vcc, s4, v130
	v_mul_f32_e32 v180, 0xbfb8aa3b, v20
	s_nop 0
	v_addc_co_u32_e32 v229, vcc, 0, v131, vcc
	s_waitcnt lgkmcnt(0)
	global_store_dwordx2 v[228:229], v[206:207], off
	v_mul_f32_e32 v206, 0xbfb8aa3b, v21
	v_mul_f32_e32 v207, 0xbfb8aa3b, v22
	v_exp_f32_e32 v180, v180
	v_exp_f32_e32 v206, v206
	v_exp_f32_e32 v207, v207
	v_rcp_f32_e32 v227, v227
	v_add_f32_e32 v180, 1.0, v180
	v_add_f32_e32 v206, 1.0, v206
	v_add_f32_e32 v207, 1.0, v207
	v_rcp_f32_e32 v180, v180
	v_rcp_f32_e32 v206, v206
	v_rcp_f32_e32 v207, v207
	s_mov_b64 s[4:5], 0xb0000
	v_cvt_pk_bf16_f32 v180, v180, v206
	v_cvt_pk_bf16_f32 v207, v207, v227
	ds_bpermute_b32 v206, v226, v180
	ds_bpermute_b32 v207, v226, v207
	v_mul_f32_e32 v180, 0xbfb8aa3b, v24
	v_mul_f32_e32 v227, 0xbfb8aa3b, v27
	v_exp_f32_e32 v180, v180
	v_exp_f32_e32 v227, v227
	s_waitcnt lgkmcnt(0)
	global_store_dwordx2 v[208:209], v[206:207], off offset:32
	v_mul_f32_e32 v206, 0xbfb8aa3b, v25
	v_mul_f32_e32 v207, 0xbfb8aa3b, v26
	v_exp_f32_e32 v206, v206
	v_exp_f32_e32 v207, v207
	v_add_f32_e32 v180, 1.0, v180
	v_add_f32_e32 v227, 1.0, v227
	v_add_f32_e32 v206, 1.0, v206
	v_add_f32_e32 v207, 1.0, v207
	v_rcp_f32_e32 v180, v180
	v_rcp_f32_e32 v206, v206
	v_rcp_f32_e32 v207, v207
	v_rcp_f32_e32 v227, v227
	v_cvt_pk_bf16_f32 v180, v180, v206
	ds_bpermute_b32 v206, v226, v180
	v_cvt_pk_bf16_f32 v207, v207, v227
	ds_bpermute_b32 v207, v226, v207
	v_mul_f32_e32 v180, 0xbfb8aa3b, v16
	v_mul_f32_e32 v227, 0xbfb8aa3b, v19
	v_exp_f32_e32 v180, v180
	v_exp_f32_e32 v227, v227
	s_waitcnt lgkmcnt(0)
	global_store_dwordx2 v[208:209], v[206:207], off offset:256
	v_mul_f32_e32 v206, 0xbfb8aa3b, v17
	v_mul_f32_e32 v207, 0xbfb8aa3b, v18
	v_exp_f32_e32 v206, v206
	v_exp_f32_e32 v207, v207
	v_add_f32_e32 v180, 1.0, v180
	v_add_f32_e32 v227, 1.0, v227
	v_add_f32_e32 v206, 1.0, v206
	v_add_f32_e32 v207, 1.0, v207
	v_rcp_f32_e32 v180, v180
	v_rcp_f32_e32 v206, v206
	v_rcp_f32_e32 v207, v207
	v_rcp_f32_e32 v227, v227
	v_cvt_pk_bf16_f32 v180, v180, v206
	ds_bpermute_b32 v206, v226, v180
	v_cvt_pk_bf16_f32 v207, v207, v227
	ds_bpermute_b32 v207, v226, v207
	v_mul_f32_e32 v180, 0xbfb8aa3b, v12
	v_exp_f32_e32 v180, v180
	s_waitcnt lgkmcnt(0)
	global_store_dwordx2 v[208:209], v[206:207], off offset:288
	v_mul_f32_e32 v206, 0xbfb8aa3b, v13
	v_mul_f32_e32 v207, 0xbfb8aa3b, v14
	v_mul_f32_e32 v208, 0xbfb8aa3b, v15
	v_exp_f32_e32 v206, v206
	v_exp_f32_e32 v207, v207
	v_exp_f32_e32 v208, v208
	v_add_f32_e32 v180, 1.0, v180
	v_add_f32_e32 v206, 1.0, v206
	v_add_f32_e32 v207, 1.0, v207
	v_add_f32_e32 v208, 1.0, v208
	v_rcp_f32_e32 v180, v180
	v_rcp_f32_e32 v206, v206
	v_rcp_f32_e32 v207, v207
	v_rcp_f32_e32 v208, v208
	v_cvt_pk_bf16_f32 v180, v180, v206
	ds_bpermute_b32 v206, v226, v180
	v_cvt_pk_bf16_f32 v207, v207, v208
	ds_bpermute_b32 v207, v226, v207
	v_lshl_add_u64 v[208:209], v[130:131], 0, s[4:5]
	s_mov_b32 s4, 0xb0000
	v_add_co_u32_e32 v130, vcc, s4, v130
	v_mul_f32_e32 v180, 0xbfb8aa3b, v6
	s_nop 0
	v_addc_co_u32_e32 v131, vcc, 0, v131, vcc
	s_waitcnt lgkmcnt(0)
	global_store_dwordx2 v[130:131], v[206:207], off
	v_mul_f32_e32 v130, 0xbfb8aa3b, v4
	v_mul_f32_e32 v131, 0xbfb8aa3b, v5
	v_mul_f32_e32 v206, 0xbfb8aa3b, v7
	v_exp_f32_e32 v130, v130
	v_exp_f32_e32 v131, v131
	v_exp_f32_e32 v180, v180
	v_exp_f32_e32 v206, v206
	v_add_f32_e32 v130, 1.0, v130
	v_add_f32_e32 v131, 1.0, v131
	v_add_f32_e32 v180, 1.0, v180
	v_add_f32_e32 v206, 1.0, v206
	v_rcp_f32_e32 v130, v130
	v_rcp_f32_e32 v131, v131
	v_rcp_f32_e32 v180, v180
	v_rcp_f32_e32 v206, v206
	s_mov_b64 s[4:5], 0
	v_cvt_pk_bf16_f32 v130, v130, v131
	ds_bpermute_b32 v130, v226, v130
	v_cvt_pk_bf16_f32 v131, v180, v206
	ds_bpermute_b32 v131, v226, v131
	v_mul_f32_e32 v180, 0xbfb8aa3b, v10
	v_mul_f32_e32 v206, 0xbfb8aa3b, v11
	v_exp_f32_e32 v180, v180
	v_exp_f32_e32 v206, v206
	s_waitcnt lgkmcnt(0)
	global_store_dwordx2 v[208:209], v[130:131], off offset:32
	v_mul_f32_e32 v130, 0xbfb8aa3b, v8
	v_mul_f32_e32 v131, 0xbfb8aa3b, v9
	v_exp_f32_e32 v130, v130
	v_exp_f32_e32 v131, v131
	v_add_f32_e32 v180, 1.0, v180
	v_add_f32_e32 v206, 1.0, v206
	v_add_f32_e32 v130, 1.0, v130
	v_add_f32_e32 v131, 1.0, v131
	v_rcp_f32_e32 v130, v130
	v_rcp_f32_e32 v131, v131
	v_rcp_f32_e32 v180, v180
	v_rcp_f32_e32 v206, v206
	v_cvt_pk_bf16_f32 v130, v130, v131
	ds_bpermute_b32 v130, v226, v130
	v_cvt_pk_bf16_f32 v131, v180, v206
	ds_bpermute_b32 v131, v226, v131
	v_mul_f32_e32 v180, 0xbfb8aa3b, v2
	v_mul_f32_e32 v206, 0xbfb8aa3b, v3
	v_exp_f32_e32 v180, v180
	v_exp_f32_e32 v206, v206
	s_waitcnt lgkmcnt(0)
	global_store_dwordx2 v[208:209], v[130:131], off offset:256
	v_mul_f32_e32 v130, 0xbfb8aa3b, v0
	v_mul_f32_e32 v131, 0xbfb8aa3b, v1
	v_exp_f32_e32 v130, v130
	v_exp_f32_e32 v131, v131
	v_add_f32_e32 v180, 1.0, v180
	v_add_f32_e32 v206, 1.0, v206
	v_add_f32_e32 v130, 1.0, v130
	v_add_f32_e32 v131, 1.0, v131
	v_rcp_f32_e32 v130, v130
	v_rcp_f32_e32 v131, v131
	v_rcp_f32_e32 v180, v180
	v_rcp_f32_e32 v206, v206
	v_cvt_pk_bf16_f32 v130, v130, v131
	ds_bpermute_b32 v130, v226, v130
	v_cvt_pk_bf16_f32 v131, v180, v206
	ds_bpermute_b32 v131, v226, v131
	s_waitcnt lgkmcnt(0)
	global_store_dwordx2 v[208:209], v[130:131], off offset:288

.LBB0_1024:
	s_waitcnt lgkmcnt(0)
	ds_read_b128 v[128:131], v179
	ds_read_b128 v[132:135], v179 offset:1024
	ds_read_b128 v[136:139], v179 offset:2048
	ds_read_b128 v[140:143], v179 offset:3072
	s_add_i32 s62, s36, 2
	s_add_u32 s37, s4, 0xfff80080
	s_addc_u32 s38, s5, -1
	s_cmp_eq_u32 s59, s36
	s_cselect_b32 s36, s58, s60
	s_cselect_b32 s39, s21, s38
	s_cselect_b32 s38, s25, s37
	s_cselect_b32 s37, s23, s61

	s_add_i32 m0, s31, 0xc000
	ds_read_b128 v[144:147], v190
	ds_read_b128 v[148:151], v190 offset:1024
	ds_read_b128 v[152:155], v190 offset:2048
	ds_read_b128 v[156:159], v190 offset:3072
	ds_read_b128 v[180:183], v190 offset:4096
	ds_read_b128 v[184:187], v190 offset:5120
	ds_read_b128 v[194:197], v190 offset:6144
	ds_read_b128 v[198:201], v190 offset:7168
	global_load_lds_dwordx4 v162, s[4:5]
	s_add_i32 m0, s31, 0xe000
	s_nop 0

	global_load_lds_dwordx4 v164, s[4:5]
	s_waitcnt lgkmcnt(8)
	s_barrier
	s_waitcnt lgkmcnt(0)


	v_mfma_f32_16x16x32_bf16 v[124:127], v[128:131], v[144:147], v[124:127]
	v_mfma_f32_16x16x32_bf16 v[120:123], v[136:139], v[144:147], v[120:123]
	v_mfma_f32_16x16x32_bf16 v[116:119], v[128:131], v[152:155], v[116:119]
	v_mfma_f32_16x16x32_bf16 v[104:107], v[136:139], v[152:155], v[104:107]
	v_mfma_f32_16x16x32_bf16 v[96:99], v[128:131], v[180:183], v[96:99]
	v_mfma_f32_16x16x32_bf16 v[88:91], v[136:139], v[180:183], v[88:91]
	v_mfma_f32_16x16x32_bf16 v[80:83], v[128:131], v[194:197], v[80:83]
	v_mfma_f32_16x16x32_bf16 v[72:75], v[136:139], v[194:197], v[72:75]
	v_mfma_f32_16x16x32_bf16 v[124:127], v[132:135], v[148:151], v[124:127]
	v_mfma_f32_16x16x32_bf16 v[120:123], v[140:143], v[148:151], v[120:123]
	v_mfma_f32_16x16x32_bf16 v[116:119], v[132:135], v[156:159], v[116:119]
	v_mfma_f32_16x16x32_bf16 v[104:107], v[140:143], v[156:159], v[104:107]
	v_mfma_f32_16x16x32_bf16 v[96:99], v[132:135], v[184:187], v[96:99]
	v_mfma_f32_16x16x32_bf16 v[88:91], v[140:143], v[184:187], v[88:91]
	v_mfma_f32_16x16x32_bf16 v[80:83], v[132:135], v[198:201], v[80:83]
	v_mfma_f32_16x16x32_bf16 v[72:75], v[140:143], v[198:201], v[72:75]

	s_barrier
	s_add_i32 s63, s52, s42
	s_add_u32 s66, s36, s14
	s_addc_u32 s67, s37, s15
	s_mov_b32 m0, s63
	ds_read_b128 v[202:205], v191
	ds_read_b128 v[206:209], v191 offset:1024
	ds_read_b128 v[222:225], v191 offset:2048
	ds_read_b128 v[226:229], v191 offset:3072
	global_load_lds_dwordx4 v172, s[36:37]
	s_add_i32 m0, s63, 0x2000
	s_nop 0

	global_load_lds_dwordx4 v174, s[36:37]
	s_barrier
	s_waitcnt lgkmcnt(0)


	v_mfma_f32_16x16x32_bf16 v[112:115], v[202:205], v[144:147], v[112:115]
	v_mfma_f32_16x16x32_bf16 v[108:111], v[222:225], v[144:147], v[108:111]
	v_mfma_f32_16x16x32_bf16 v[100:103], v[202:205], v[152:155], v[100:103]
	v_mfma_f32_16x16x32_bf16 v[92:95], v[222:225], v[152:155], v[92:95]
	v_mfma_f32_16x16x32_bf16 v[84:87], v[202:205], v[180:183], v[84:87]
	v_mfma_f32_16x16x32_bf16 v[76:79], v[222:225], v[180:183], v[76:79]
	v_mfma_f32_16x16x32_bf16 v[68:71], v[202:205], v[194:197], v[68:71]
	v_mfma_f32_16x16x32_bf16 v[64:67], v[222:225], v[194:197], v[64:67]
	v_mfma_f32_16x16x32_bf16 v[112:115], v[206:209], v[148:151], v[112:115]
	v_mfma_f32_16x16x32_bf16 v[108:111], v[226:229], v[148:151], v[108:111]
	v_mfma_f32_16x16x32_bf16 v[100:103], v[206:209], v[156:159], v[100:103]
	v_mfma_f32_16x16x32_bf16 v[92:95], v[226:229], v[156:159], v[92:95]
	v_mfma_f32_16x16x32_bf16 v[84:87], v[206:209], v[184:187], v[84:87]
	v_mfma_f32_16x16x32_bf16 v[76:79], v[226:229], v[184:187], v[76:79]
	v_mfma_f32_16x16x32_bf16 v[68:71], v[206:209], v[198:201], v[68:71]
	v_mfma_f32_16x16x32_bf16 v[64:67], v[226:229], v[198:201], v[64:67]

	s_mov_b32 m0, s31
	s_add_u32 s68, s38, s14
	s_addc_u32 s69, s39, s15
	s_barrier
	ds_read_b128 v[144:147], v190 offset:16384
	ds_read_b128 v[148:151], v190 offset:17408
	ds_read_b128 v[152:155], v190 offset:18432
	ds_read_b128 v[156:159], v190 offset:19456
	ds_read_b128 v[180:183], v190 offset:20480
	ds_read_b128 v[184:187], v190 offset:21504
	ds_read_b128 v[194:197], v190 offset:22528
	ds_read_b128 v[198:201], v190 offset:23552
	global_load_lds_dwordx4 v172, s[38:39]
	s_mov_b32 m0, s35
	s_nop 0

	global_load_lds_dwordx4 v174, s[38:39]
	s_barrier
	s_waitcnt lgkmcnt(0)


	v_mfma_f32_16x16x32_bf16 v[60:63], v[128:131], v[144:147], v[60:63]
	v_mfma_f32_16x16x32_bf16 v[56:59], v[136:139], v[144:147], v[56:59]
	v_mfma_f32_16x16x32_bf16 v[52:55], v[128:131], v[152:155], v[52:55]
	v_mfma_f32_16x16x32_bf16 v[40:43], v[136:139], v[152:155], v[40:43]
	v_mfma_f32_16x16x32_bf16 v[36:39], v[128:131], v[180:183], v[36:39]
	v_mfma_f32_16x16x32_bf16 v[24:27], v[136:139], v[180:183], v[24:27]
	v_mfma_f32_16x16x32_bf16 v[20:23], v[128:131], v[194:197], v[20:23]
	v_mfma_f32_16x16x32_bf16 v[8:11], v[136:139], v[194:197], v[8:11]
	v_mfma_f32_16x16x32_bf16 v[60:63], v[132:135], v[148:151], v[60:63]
	v_mfma_f32_16x16x32_bf16 v[56:59], v[140:143], v[148:151], v[56:59]
	v_mfma_f32_16x16x32_bf16 v[52:55], v[132:135], v[156:159], v[52:55]
	v_mfma_f32_16x16x32_bf16 v[40:43], v[140:143], v[156:159], v[40:43]
	v_mfma_f32_16x16x32_bf16 v[36:39], v[132:135], v[184:187], v[36:39]
	v_mfma_f32_16x16x32_bf16 v[24:27], v[140:143], v[184:187], v[24:27]
	v_mfma_f32_16x16x32_bf16 v[20:23], v[132:135], v[198:201], v[20:23]
	v_mfma_f32_16x16x32_bf16 v[8:11], v[140:143], v[198:201], v[8:11]

	s_barrier
	s_add_u32 s64, s36, 0x80000
	s_addc_u32 s65, s37, 0
	s_add_i32 s63, s53, s42
	s_mov_b32 m0, s63
	s_nop 0

	global_load_lds_dwordx4 v172, s[64:65]
	s_add_i32 m0, s63, 0x2000
	s_nop 0

	global_load_lds_dwordx4 v174, s[64:65]
	s_waitcnt vmcnt(6)
	s_barrier

	v_mfma_f32_16x16x32_bf16 v[48:51], v[202:205], v[144:147], v[48:51]
	v_mfma_f32_16x16x32_bf16 v[44:47], v[222:225], v[144:147], v[44:47]
	v_mfma_f32_16x16x32_bf16 v[32:35], v[202:205], v[152:155], v[32:35]
	v_mfma_f32_16x16x32_bf16 v[28:31], v[222:225], v[152:155], v[28:31]
	v_mfma_f32_16x16x32_bf16 v[16:19], v[202:205], v[180:183], v[16:19]
	v_mfma_f32_16x16x32_bf16 v[12:15], v[222:225], v[180:183], v[12:15]
	v_mfma_f32_16x16x32_bf16 v[4:7], v[202:205], v[194:197], v[4:7]
	v_mfma_f32_16x16x32_bf16 v[0:3], v[222:225], v[194:197], v[0:3]
	v_mfma_f32_16x16x32_bf16 v[48:51], v[206:209], v[148:151], v[48:51]
	v_mfma_f32_16x16x32_bf16 v[44:47], v[226:229], v[148:151], v[44:47]
	v_mfma_f32_16x16x32_bf16 v[32:35], v[206:209], v[156:159], v[32:35]
	v_mfma_f32_16x16x32_bf16 v[28:31], v[226:229], v[156:159], v[28:31]
	v_mfma_f32_16x16x32_bf16 v[16:19], v[206:209], v[184:187], v[16:19]
	v_mfma_f32_16x16x32_bf16 v[12:15], v[226:229], v[184:187], v[12:15]
	v_mfma_f32_16x16x32_bf16 v[4:7], v[206:209], v[198:201], v[4:7]
	v_mfma_f32_16x16x32_bf16 v[0:3], v[226:229], v[198:201], v[0:3]

	s_add_i32 s63, 0, 0x18000

	s_barrier
	ds_read_b128 v[128:131], v179 offset:32768
	ds_read_b128 v[132:135], v179 offset:33792
	ds_read_b128 v[136:139], v179 offset:34816
	ds_read_b128 v[140:143], v179 offset:35840
	s_add_u32 s38, s38, 0x80000
	s_addc_u32 s39, s39, 0
	s_mov_b32 m0, s43

	ds_read_b128 v[144:147], v190 offset:32768
	ds_read_b128 v[148:151], v190 offset:33792
	ds_read_b128 v[152:155], v190 offset:34816
	ds_read_b128 v[156:159], v190 offset:35840
	ds_read_b128 v[180:183], v190 offset:36864
	ds_read_b128 v[184:187], v190 offset:37888
	ds_read_b128 v[194:197], v190 offset:38912
	ds_read_b128 v[198:201], v190 offset:39936
	global_load_lds_dwordx4 v172, s[38:39]
	s_mov_b32 m0, s44
	s_nop 0

	global_load_lds_dwordx4 v174, s[38:39]
	s_waitcnt lgkmcnt(8)
	s_barrier
	s_waitcnt lgkmcnt(0)


	v_mfma_f32_16x16x32_bf16 v[124:127], v[128:131], v[144:147], v[124:127]
	v_mfma_f32_16x16x32_bf16 v[120:123], v[136:139], v[144:147], v[120:123]
	v_mfma_f32_16x16x32_bf16 v[116:119], v[128:131], v[152:155], v[116:119]
	v_mfma_f32_16x16x32_bf16 v[104:107], v[136:139], v[152:155], v[104:107]
	v_mfma_f32_16x16x32_bf16 v[96:99], v[128:131], v[180:183], v[96:99]
	v_mfma_f32_16x16x32_bf16 v[88:91], v[136:139], v[180:183], v[88:91]
	v_mfma_f32_16x16x32_bf16 v[80:83], v[128:131], v[194:197], v[80:83]
	v_mfma_f32_16x16x32_bf16 v[72:75], v[136:139], v[194:197], v[72:75]
	v_mfma_f32_16x16x32_bf16 v[124:127], v[132:135], v[148:151], v[124:127]
	v_mfma_f32_16x16x32_bf16 v[120:123], v[140:143], v[148:151], v[120:123]
	v_mfma_f32_16x16x32_bf16 v[116:119], v[132:135], v[156:159], v[116:119]
	v_mfma_f32_16x16x32_bf16 v[104:107], v[140:143], v[156:159], v[104:107]
	v_mfma_f32_16x16x32_bf16 v[96:99], v[132:135], v[184:187], v[96:99]
	v_mfma_f32_16x16x32_bf16 v[88:91], v[140:143], v[184:187], v[88:91]
	v_mfma_f32_16x16x32_bf16 v[80:83], v[132:135], v[198:201], v[80:83]
	v_mfma_f32_16x16x32_bf16 v[72:75], v[140:143], v[198:201], v[72:75]

	s_barrier
	s_add_i32 s38, 0, 0x1c000
	s_add_i32 s39, s63, s42


	s_mov_b32 m0, s39
	ds_read_b128 v[202:205], v191 offset:32768
	ds_read_b128 v[206:209], v191 offset:33792
	ds_read_b128 v[222:225], v191 offset:34816
	ds_read_b128 v[226:229], v191 offset:35840
	global_load_lds_dwordx4 v172, s[66:67]
	s_add_i32 m0, s39, 0x2000
	s_nop 0

	global_load_lds_dwordx4 v174, s[66:67]
	s_barrier
	s_waitcnt lgkmcnt(0)


	v_mfma_f32_16x16x32_bf16 v[112:115], v[202:205], v[144:147], v[112:115]
	v_mfma_f32_16x16x32_bf16 v[108:111], v[222:225], v[144:147], v[108:111]
	v_mfma_f32_16x16x32_bf16 v[100:103], v[202:205], v[152:155], v[100:103]
	v_mfma_f32_16x16x32_bf16 v[92:95], v[222:225], v[152:155], v[92:95]
	v_mfma_f32_16x16x32_bf16 v[84:87], v[202:205], v[180:183], v[84:87]
	v_mfma_f32_16x16x32_bf16 v[76:79], v[222:225], v[180:183], v[76:79]
	v_mfma_f32_16x16x32_bf16 v[68:71], v[202:205], v[194:197], v[68:71]
	v_mfma_f32_16x16x32_bf16 v[64:67], v[222:225], v[194:197], v[64:67]
	v_mfma_f32_16x16x32_bf16 v[112:115], v[206:209], v[148:151], v[112:115]
	v_mfma_f32_16x16x32_bf16 v[108:111], v[226:229], v[148:151], v[108:111]
	v_mfma_f32_16x16x32_bf16 v[100:103], v[206:209], v[156:159], v[100:103]
	v_mfma_f32_16x16x32_bf16 v[92:95], v[226:229], v[156:159], v[92:95]
	v_mfma_f32_16x16x32_bf16 v[84:87], v[206:209], v[184:187], v[84:87]
	v_mfma_f32_16x16x32_bf16 v[76:79], v[226:229], v[184:187], v[76:79]
	v_mfma_f32_16x16x32_bf16 v[68:71], v[206:209], v[198:201], v[68:71]
	v_mfma_f32_16x16x32_bf16 v[64:67], v[226:229], v[198:201], v[64:67]

	s_mov_b32 m0, s48

	s_barrier
	ds_read_b128 v[144:147], v190 offset:49152
	ds_read_b128 v[148:151], v190 offset:50176
	ds_read_b128 v[152:155], v190 offset:51200
	ds_read_b128 v[156:159], v190 offset:52224
	ds_read_b128 v[180:183], v190 offset:53248
	ds_read_b128 v[184:187], v190 offset:54272
	ds_read_b128 v[194:197], v190 offset:55296
	ds_read_b128 v[198:201], v190 offset:56320
	global_load_lds_dwordx4 v172, s[68:69]
	s_mov_b32 m0, s49
	s_nop 0

	global_load_lds_dwordx4 v174, s[68:69]
	s_barrier
	s_waitcnt lgkmcnt(0)


	v_mfma_f32_16x16x32_bf16 v[60:63], v[128:131], v[144:147], v[60:63]
	v_mfma_f32_16x16x32_bf16 v[56:59], v[136:139], v[144:147], v[56:59]
	v_mfma_f32_16x16x32_bf16 v[52:55], v[128:131], v[152:155], v[52:55]
	v_mfma_f32_16x16x32_bf16 v[40:43], v[136:139], v[152:155], v[40:43]
	v_mfma_f32_16x16x32_bf16 v[36:39], v[128:131], v[180:183], v[36:39]
	v_mfma_f32_16x16x32_bf16 v[24:27], v[136:139], v[180:183], v[24:27]
	v_mfma_f32_16x16x32_bf16 v[20:23], v[128:131], v[194:197], v[20:23]
	v_mfma_f32_16x16x32_bf16 v[8:11], v[136:139], v[194:197], v[8:11]
	v_mfma_f32_16x16x32_bf16 v[60:63], v[132:135], v[148:151], v[60:63]
	v_mfma_f32_16x16x32_bf16 v[56:59], v[140:143], v[148:151], v[56:59]
	v_mfma_f32_16x16x32_bf16 v[52:55], v[132:135], v[156:159], v[52:55]
	v_mfma_f32_16x16x32_bf16 v[40:43], v[140:143], v[156:159], v[40:43]
	v_mfma_f32_16x16x32_bf16 v[36:39], v[132:135], v[184:187], v[36:39]
	v_mfma_f32_16x16x32_bf16 v[24:27], v[140:143], v[184:187], v[24:27]
	v_mfma_f32_16x16x32_bf16 v[20:23], v[132:135], v[198:201], v[20:23]
	v_mfma_f32_16x16x32_bf16 v[8:11], v[140:143], v[198:201], v[8:11]

	s_barrier
	s_add_u32 s36, s36, 0x80080
	s_addc_u32 s37, s37, 0
	s_add_i32 s38, s38, s42
	s_mov_b32 m0, s38
	s_nop 0

	global_load_lds_dwordx4 v172, s[36:37]
	s_add_i32 m0, s38, 0x2000
	s_nop 0

	global_load_lds_dwordx4 v174, s[36:37]
	s_waitcnt vmcnt(6)
	s_barrier

	v_mfma_f32_16x16x32_bf16 v[48:51], v[202:205], v[144:147], v[48:51]
	v_mfma_f32_16x16x32_bf16 v[44:47], v[222:225], v[144:147], v[44:47]
	v_mfma_f32_16x16x32_bf16 v[32:35], v[202:205], v[152:155], v[32:35]
	v_mfma_f32_16x16x32_bf16 v[28:31], v[222:225], v[152:155], v[28:31]
	v_mfma_f32_16x16x32_bf16 v[16:19], v[202:205], v[180:183], v[16:19]
	v_mfma_f32_16x16x32_bf16 v[12:15], v[222:225], v[180:183], v[12:15]
	v_mfma_f32_16x16x32_bf16 v[4:7], v[202:205], v[194:197], v[4:7]
	v_mfma_f32_16x16x32_bf16 v[0:3], v[222:225], v[194:197], v[0:3]
	v_mfma_f32_16x16x32_bf16 v[48:51], v[206:209], v[148:151], v[48:51]
	v_mfma_f32_16x16x32_bf16 v[44:47], v[226:229], v[148:151], v[44:47]
	v_mfma_f32_16x16x32_bf16 v[32:35], v[206:209], v[156:159], v[32:35]
	v_mfma_f32_16x16x32_bf16 v[28:31], v[226:229], v[156:159], v[28:31]
	v_mfma_f32_16x16x32_bf16 v[16:19], v[206:209], v[184:187], v[16:19]
	v_mfma_f32_16x16x32_bf16 v[12:15], v[226:229], v[184:187], v[12:15]
	v_mfma_f32_16x16x32_bf16 v[4:7], v[206:209], v[198:201], v[4:7]
	v_mfma_f32_16x16x32_bf16 v[0:3], v[226:229], v[198:201], v[0:3]

	s_add_u32 s4, s4, 0x100
	s_addc_u32 s5, s5, 0
	s_add_u32 s60, s60, 0x100
	s_addc_u32 s61, s61, 0
	s_cmp_ge_i32 s62, s17
	s_mov_b32 s36, s62
	s_barrier
	s_cbranch_scc0 .LBB0_1024
	v_mov_b32_e32 v128, v210
	v_mov_b32_e32 v129, v169
	s_cmp_lt_i32 s12, 0
	v_lshl_add_u32 v128, v128, 4, v129
	v_ashrrev_i32_e32 v166, 2, v128
	v_and_b32_e32 v160, 3, v129
	v_and_b32_e32 v128, -4, v128
	v_lshl_add_u32 v193, v160, 6, v128
	s_mov_b64 s[4:5], -1
	s_cbranch_scc0 .LBB0_1043
	s_lshl_b32 s4, s30, 8
	v_lshl_or_b32 v128, v160, 2, s4
	s_lshl_b32 s4, s34, 8
	v_or_b32_e32 v180, s47, v128
	s_add_i32 s4, s4, s46
	v_readlane_b32 s60, v254, 6
	v_ashrrev_i32_e32 v181, 31, v180
	v_add_u32_e32 v184, s4, v166
	s_cmp_lt_i32 s34, 32
	v_readlane_b32 s61, v254, 7
	v_lshlrev_b64 v[128:129], 2, v[180:181]
	v_readlane_b32 s62, v254, 8
	v_readlane_b32 s63, v254, 9
	v_readlane_b32 s64, v254, 10
	v_readlane_b32 s65, v254, 11
	v_readlane_b32 s66, v254, 12
	v_readlane_b32 s67, v254, 13
	v_readlane_b32 s68, v254, 14
	v_readlane_b32 s69, v254, 15
	v_readlane_b32 s70, v254, 16
	v_readlane_b32 s71, v254, 17
	v_readlane_b32 s72, v254, 18
	v_readlane_b32 s73, v254, 19
	v_readlane_b32 s74, v254, 20
	v_readlane_b32 s75, v254, 21
	s_cselect_b32 s5, s61, s51
	s_cselect_b32 s4, s60, s50
	v_ashrrev_i32_e32 v185, 31, v184
	v_lshl_add_u64 v[182:183], s[4:5], 0, v[128:129]
	v_lshlrev_b64 v[130:131], 13, v[184:185]
	v_readlane_b32 s60, v254, 22
	v_lshl_add_u64 v[136:137], v[182:183], 0, v[130:131]
	v_readlane_b32 s61, v254, 23
	v_readlane_b32 s68, v254, 30
	v_readlane_b32 s69, v254, 31
	global_load_dwordx4 v[196:199], v[136:137], off nt
	global_load_dwordx4 v[200:203], v[136:137], off offset:64 nt
	global_load_dwordx4 v[204:207], v[136:137], off offset:512 nt
	s_mov_b64 s[60:61], s[68:69]
	v_lshl_add_u64 v[138:139], s[60:61], 0, v[128:129]
	global_load_dwordx4 v[140:143], v[138:139], off
	global_load_dwordx4 v[132:135], v[138:139], off offset:64
	global_load_dwordx4 v[128:131], v[138:139], off offset:512
	global_load_dwordx4 v[222:225], v[136:137], off offset:576 nt
	v_and_b32_e32 v145, 64, v192
	global_load_dwordx4 v[136:139], v[138:139], off offset:576
	v_xor_b32_e32 v144, 1, v192
	v_add_u32_e32 v194, 64, v145
	v_add_u32_e32 v186, 16, v184
	v_cmp_lt_i32_e64 s[4:5], v144, v194
	v_ashrrev_i32_e32 v187, 31, v186
	ds_bpermute_b32 v188, v193, v124
	v_cndmask_b32_e64 v195, v192, v144, s[4:5]
	v_lshlrev_b64 v[144:145], 13, v[186:187]
	v_lshl_add_u64 v[144:145], v[182:183], 0, v[144:145]
	global_load_dwordx4 v[156:159], v[144:145], off nt
	global_load_dwordx4 v[152:155], v[144:145], off offset:64 nt
	global_load_dwordx4 v[148:151], v[144:145], off offset:512 nt
	s_nop 0
	global_load_dwordx4 v[144:147], v[144:145], off offset:576 nt
	ds_bpermute_b32 v189, v193, v125
	ds_bpermute_b32 v208, v193, v126
	ds_bpermute_b32 v209, v193, v127
	ds_bpermute_b32 v226, v193, v120
	ds_bpermute_b32 v227, v193, v121
	ds_bpermute_b32 v228, v193, v122
	ds_bpermute_b32 v229, v193, v123
	ds_bpermute_b32 v230, v193, v112
	ds_bpermute_b32 v231, v193, v113
	v_readlane_b32 s64, v254, 26
	v_readlane_b32 s65, v254, 27
	v_readlane_b32 s66, v254, 28
	v_readlane_b32 s67, v254, 29
	v_readlane_b32 s72, v254, 34
	v_readlane_b32 s73, v254, 35
	v_readlane_b32 s74, v254, 36
	v_readlane_b32 s75, v254, 37
	s_mov_b64 s[64:65], s[72:73]
	ds_bpermute_b32 v232, v193, v114
	ds_bpermute_b32 v233, v193, v115
	v_lshlrev_b64 v[234:235], 11, v[184:185]
	s_mov_b64 s[66:67], s[74:75]
	v_lshl_add_u64 v[234:235], v[234:235], 0, v[180:181]
	v_xor_b32_e32 v167, 2, v192
	v_lshl_add_u64 v[236:237], v[234:235], 2, s[66:67]
	v_readlane_b32 s2, v254, 54
	v_cmp_lt_i32_e64 s[4:5], v167, v194
	v_lshlrev_b32_e32 v194, 2, v195
	v_lshlrev_b64 v[234:235], 1, v[234:235]
	v_readlane_b32 s3, v254, 55
	v_or_b32_e32 v240, 32, v234
	v_mov_b32_e32 v241, v235
	v_lshl_add_u64 v[238:239], s[2:3], 0, v[234:235]
	v_lshl_add_u64 v[240:241], s[2:3], 0, v[240:241]
	v_cndmask_b32_e64 v167, v192, v167, s[4:5]
	v_lshlrev_b32_e32 v167, 2, v167
	v_cmp_eq_u32_e32 vcc, 0, v160
	v_readlane_b32 s62, v254, 24
	v_readlane_b32 s63, v254, 25
	v_readlane_b32 s70, v254, 32
	v_readlane_b32 s71, v254, 33
	s_waitcnt vmcnt(0) lgkmcnt(0)
	v_pk_add_f32 v[198:199], v[198:199], v[208:209]
	v_pk_add_f32 v[196:197], v[196:197], v[188:189]
	v_pk_add_f32 v[202:203], v[202:203], v[228:229]
	v_pk_add_f32 v[200:201], v[200:201], v[226:227]
	v_pk_add_f32 v[204:205], v[204:205], v[230:231]
	v_mul_f32_e32 v195, v197, v197
	v_mul_f32_e32 v221, v199, v199
	global_store_dwordx4 v[236:237], v[196:199], off
	v_pk_mul_f32 v[188:189], v[142:143], v[198:199]
	v_pk_mul_f32 v[208:209], v[140:141], v[196:197]
	v_mul_f32_e32 v199, v201, v201
	v_mul_f32_e32 v230, v203, v203
	v_pk_mul_f32 v[226:227], v[134:135], v[202:203]
	v_pk_mul_f32 v[228:229], v[132:133], v[200:201]
	v_fmac_f32_e32 v195, v196, v196
	v_fmac_f32_e32 v221, v198, v198
	v_cvt_pk_bf16_f32 v196, v208, v209
	v_cvt_pk_bf16_f32 v197, v188, v189
	v_fmac_f32_e32 v199, v200, v200
	v_fmac_f32_e32 v230, v202, v202
	v_pk_add_f32 v[206:207], v[206:207], v[232:233]
	v_cvt_pk_bf16_f32 v188, v228, v229
	v_cvt_pk_bf16_f32 v189, v226, v227
	v_add_f32_e32 v195, v195, v221
	global_store_dwordx2 v[238:239], v[196:197], off
	v_add_f32_e32 v196, v199, v230
	global_store_dwordx4 v[236:237], v[200:203], off offset:64
	global_store_dwordx2 v[240:241], v[188:189], off
	v_add_f32_e32 v188, v195, v196
	v_mul_f32_e32 v189, v205, v205
	v_mul_f32_e32 v195, v207, v207
	v_fmac_f32_e32 v189, v204, v204
	v_fmac_f32_e32 v195, v206, v206
	ds_bpermute_b32 v200, v193, v108
	ds_bpermute_b32 v198, v193, v110
	ds_bpermute_b32 v199, v193, v111
	ds_bpermute_b32 v201, v193, v109
	v_add_f32_e32 v189, v189, v195
	v_add_f32_e32 v195, v188, v189
	v_pk_mul_f32 v[188:189], v[130:131], v[206:207]
	v_pk_mul_f32 v[196:197], v[128:129], v[204:205]
	global_store_dwordx4 v[236:237], v[204:207], off offset:512
	v_cvt_pk_bf16_f32 v196, v196, v197
	v_cvt_pk_bf16_f32 v197, v188, v189
	v_or_b32_e32 v188, 0x100, v234
	v_mov_b32_e32 v189, v235
	v_lshl_add_u64 v[188:189], s[2:3], 0, v[188:189]
	global_store_dwordx2 v[188:189], v[196:197], off
	s_waitcnt lgkmcnt(1)
	v_pk_add_f32 v[198:199], v[224:225], v[198:199]
	s_waitcnt lgkmcnt(0)
	v_pk_add_f32 v[196:197], v[222:223], v[200:201]
	v_mul_f32_e32 v189, v199, v199
	v_mul_f32_e32 v188, v197, v197
	v_fmac_f32_e32 v188, v196, v196
	v_fmac_f32_e32 v189, v198, v198
	v_add_f32_e32 v188, v188, v189
	v_add_f32_e32 v195, v195, v188
	ds_bpermute_b32 v200, v194, v195
	v_pk_mul_f32 v[188:189], v[136:137], v[196:197]
	global_store_dwordx4 v[236:237], v[196:199], off offset:576
	v_or_b32_e32 v234, 0x120, v234
	s_nop 0
	v_cvt_pk_bf16_f32 v196, v188, v189
	s_waitcnt lgkmcnt(0)
	v_add_f32_e32 v188, v195, v200
	ds_bpermute_b32 v189, v167, v188
	v_pk_mul_f32 v[198:199], v[138:139], v[198:199]
	s_nop 0
	v_cvt_pk_bf16_f32 v197, v198, v199
	v_lshl_add_u64 v[198:199], s[2:3], 0, v[234:235]
	global_store_dwordx2 v[198:199], v[196:197], off
	s_and_saveexec_b64 s[4:5], vcc
	s_cbranch_execz .LBB0_1028
	s_waitcnt lgkmcnt(0)
	v_add_f32_e32 v195, v188, v189
	s_lshl_b32 s36, s30, 2
	v_lshlrev_b64 v[188:189], 7, v[184:185]
	s_ashr_i32 s37, s36, 31
	v_lshl_add_u64 v[188:189], s[10:11], 0, v[188:189]
	v_lshl_add_u64 v[188:189], s[36:37], 2, v[188:189]
	s_lshl_b32 s36, s45, 2
	s_mov_b32 s37, s13
	v_lshl_add_u64 v[188:189], v[188:189], 0, s[36:37]
	global_store_dword v[188:189], v195, off
